# on top of previous: removed the redundant vmcnt(0) wait between the top-generation release atomic and the local-release atomic in the barrier leader path
# baseline (speedup 1.0000x reference)
; __device__ __forceinline__ unsigned xb_ld(unsigned* p)              { return __hip_atomic_load(p, __ATOMIC_RELAXED, __HIP_MEMORY_SCOPE_AGENT); }
; __device__ __forceinline__ unsigned xb_add(unsigned* p, unsigned v) { return __hip_atomic_fetch_add(p, v, __ATOMIC_RELAXED, __HIP_MEMORY_SCOPE_AGENT); }
; #define XB_SPIN(cond, bar) do { unsigned _sp = 0; while (cond) { __builtin_amdgcn_s_sleep(1); \
;     if ((++_sp & 255u) == 0u) { if (xb_ld(&(bar)[XB_TMO])) break; if (_sp > XB_SPIN_CAP) { atomicAdd(&(bar)[XB_TMO], 1u); break; } } } } while (0)
; __device__ __forceinline__ void xcd_barrier(const XcdBarrier& b) {
;     ...
;             __builtin_amdgcn_fence(__ATOMIC_RELEASE, "agent");
;             asm volatile("s_waitcnt vmcnt(0)" ::: "memory");
;             const unsigned og = xb_add(&bar[XB_TOP], 1u);
;             const unsigned tg = og / nx;
;             if (og + 1u == (tg + 1u) * nx) xb_add(&bar[XB_TOPGEN], 1u);
;             else XB_SPIN(xb_ld(&bar[XB_TOPGEN]) == tg, bar);
;             __builtin_amdgcn_fence(__ATOMIC_ACQUIRE, "agent");
;             xb_add(&bar[XB_XGEN(b.x)], 1u);
;             asm volatile("s_waitcnt vmcnt(0)" ::: "memory");
.LBB0_36:
	s_or_b64 exec, exec, s[2:3]
	v_mov_b32_e32 v1, s23
	v_add_co_u32_e32 v2, vcc, 0x2000, v1
	v_mov_b32_e32 v1, s22
	s_nop 0
	v_addc_co_u32_e32 v3, vcc, 0, v1, vcc
	flat_atomic_add v[2:3], v243 offset:1024
	buffer_inv sc1
	s_waitcnt vmcnt(0)
